# attnB: unchecked tile-loop copy as well (sink reference + gain bound proven in the phase prologue), on top of the attnA unchecked loop
# speedup vs baseline: 1.0129x; 1.0070x over previous
.LBB0_444:
	s_andn2_b64 vcc, exec, s[44:45]
	s_cbranch_vccnz .LBB0_501
	v_readlane_b32 s0, v241, 40
	v_readlane_b32 s1, v241, 41
	s_mov_b64 s[4:5], -1
	s_and_b64 vcc, exec, s[0:1]
	s_cbranch_vccz .LBB0_471
	v_readlane_b32 s0, v242, 17
	v_mov_b32_e32 v2, v0
	v_readlane_b32 s1, v242, 18
	s_mov_b32 s34, s6
	s_andn2_b64 vcc, exec, s[0:1]
	v_readfirstlane_b32 s1, v2
	s_cbranch_vccnz .LBB0_470
	v_ashrrev_i32_e32 v3, 31, v2
	v_lshrrev_b32_e32 v3, 29, v3
	v_add_u32_e32 v3, v2, v3
	v_ashrrev_i32_e32 v157, 3, v3
	v_and_b32_e32 v3, -8, v3
	v_readlane_b32 s4, v241, 38
	v_sub_u32_e32 v3, v2, v3
	s_movk_i32 s6, 0x90
	v_readlane_b32 s5, v241, 39
	v_lshlrev_b32_e32 v158, 3, v3
	v_ashrrev_i32_e32 v7, 3, v2
	v_mul_lo_u32 v9, v157, s6
	v_lshlrev_b32_e32 v3, 4, v3
	s_load_dwordx2 s[4:5], s[4:5], 0xa0
	v_bfe_u32 v5, v2, 5, 1
	v_and_b32_e32 v6, 31, v2
	v_lshlrev_b32_e32 v8, 3, v2
	s_waitcnt vmcnt(0)
	v_add3_u32 v170, 0, v9, v3
	v_mul_lo_u32 v3, v7, s6
	v_lshlrev_b32_e32 v2, 4, v2
	s_ashr_i32 s0, s1, 8
	s_lshr_b32 s1, s1, 1
	v_and_b32_e32 v4, 56, v8
	v_add_u32_e32 v3, 0, v3
	v_and_b32_e32 v2, 0x60, v2
	v_and_b32_e32 v8, 8, v8
	v_readlane_b32 s6, v241, 45
	s_and_b32 s3, s1, 0x60
	v_add3_u32 v171, v3, v2, v8
	v_mul_u32_u24_e32 v2, 0x90, v6
	v_lshlrev_b32_e32 v3, 4, v5
	v_readlane_b32 s7, v241, 46
	s_add_u32 s1, s74, 0x7e00800
	v_add3_u32 v172, 0, v2, v3
	v_mov_b64_e32 v[2:3], s[6:7]
	s_movk_i32 s6, 0x2200
	v_lshlrev_b32_e32 v156, 3, v5
	s_addc_u32 s10, s75, 0
	v_ashrrev_i32_e32 v159, 31, v158
	v_mad_i64_i32 v[160:161], s[6:7], v7, s6, v[2:3]
	v_or_b32_e32 v173, s3, v6
	v_lshl_add_u32 v174, v5, 2, v224
	v_lshlrev_b32_e32 v184, 1, v4
	v_readlane_b32 s44, v241, 38
	v_readlane_b32 s45, v241, 39
	s_nop 0
	s_load_dwordx4 s[44:47], s[44:45], 0x90
	v_and_b32_e32 v40, 63, v0
	v_lshlrev_b32_e32 v40, 2, v40
	s_waitcnt lgkmcnt(0)
	global_load_dword v41, v40, s[44:45]
	global_load_dword v42, v40, s[46:47]
	v_readlane_b32 s44, v241, 38
	v_readlane_b32 s45, v241, 39
	s_nop 0
	s_load_dwordx2 s[44:45], s[44:45], 0xa0
	v_and_b32_e32 v46, 15, v0
	v_lshlrev_b32_e32 v46, 2, v46
	s_waitcnt lgkmcnt(0)
	global_load_dword v47, v46, s[44:45]
	s_waitcnt vmcnt(0)
	v_and_b32_e32 v41, 0x7fffffff, v41
	v_and_b32_e32 v42, 0x7fffffff, v42
	v_and_b32_e32 v47, 0x7fffffff, v47
	v_xor_b32_e32 v43, 1, v223
	v_lshlrev_b32_e32 v43, 2, v43
	ds_bpermute_b32 v44, v43, v41
	ds_bpermute_b32 v45, v43, v42
	ds_bpermute_b32 v46, v43, v47
	s_waitcnt lgkmcnt(0)
	v_max_f32_e32 v41, v41, v44
	v_max_f32_e32 v42, v42, v45
	v_max_f32_e32 v47, v47, v46
	v_xor_b32_e32 v43, 2, v223
	v_lshlrev_b32_e32 v43, 2, v43
	ds_bpermute_b32 v44, v43, v41
	ds_bpermute_b32 v45, v43, v42
	ds_bpermute_b32 v46, v43, v47
	s_waitcnt lgkmcnt(0)
	v_max_f32_e32 v41, v41, v44
	v_max_f32_e32 v42, v42, v45
	v_max_f32_e32 v47, v47, v46
	v_xor_b32_e32 v43, 4, v223
	v_lshlrev_b32_e32 v43, 2, v43
	ds_bpermute_b32 v44, v43, v41
	ds_bpermute_b32 v45, v43, v42
	ds_bpermute_b32 v46, v43, v47
	s_waitcnt lgkmcnt(0)
	v_max_f32_e32 v41, v41, v44
	v_max_f32_e32 v42, v42, v45
	v_max_f32_e32 v47, v47, v46
	v_xor_b32_e32 v43, 8, v223
	v_lshlrev_b32_e32 v43, 2, v43
	ds_bpermute_b32 v44, v43, v41
	ds_bpermute_b32 v45, v43, v42
	ds_bpermute_b32 v46, v43, v47
	s_waitcnt lgkmcnt(0)
	v_max_f32_e32 v41, v41, v44
	v_max_f32_e32 v42, v42, v45
	v_max_f32_e32 v47, v47, v46
	v_xor_b32_e32 v43, 16, v223
	v_lshlrev_b32_e32 v43, 2, v43
	ds_bpermute_b32 v44, v43, v41
	ds_bpermute_b32 v45, v43, v42
	ds_bpermute_b32 v46, v43, v47
	s_waitcnt lgkmcnt(0)
	v_max_f32_e32 v41, v41, v44
	v_max_f32_e32 v42, v42, v45
	v_max_f32_e32 v47, v47, v46
	v_xor_b32_e32 v43, 32, v223
	v_lshlrev_b32_e32 v43, 2, v43
	ds_bpermute_b32 v44, v43, v41
	ds_bpermute_b32 v45, v43, v42
	ds_bpermute_b32 v46, v43, v47
	s_waitcnt lgkmcnt(0)
	v_max_f32_e32 v41, v41, v44
	v_max_f32_e32 v42, v42, v45
	v_max_f32_e32 v47, v47, v46
	v_mul_f32_e32 v41, v41, v42
	v_mul_f32_e32 v41, 0x4138aa3b, v41
	v_fmac_f32_e32 v41, 0x3fb8aa3b, v47
	v_cmp_gt_f32_e32 vcc, 0x42700000, v41
	s_nop 3
	s_cmp_lg_u64 vcc, 0
	s_cselect_b32 s101, 1, 0
	s_mov_b32 s11, s2
	s_branch .LBB0_450

.LBB0_458:
	v_add_u32_e32 v5, s27, v157
	v_mov_b64_e32 v[6:7], s[20:21]
	v_mad_i64_i32 v[6:7], s[22:23], v5, s60, v[6:7]
	v_lshl_add_u64 v[6:7], v[158:159], 1, v[6:7]
	v_lshl_add_u64 v[8:9], s[78:79], 1, v[2:3]
	v_lshl_add_u64 v[8:9], v[8:9], 0, v[184:185]
	global_load_dwordx4 v[148:151], v[6:7], off
	global_load_dwordx4 v[152:155], v[8:9], off
	s_cmp_lt_i32 s17, -3
	s_waitcnt lgkmcnt(0)
	s_barrier
	s_cbranch_scc1 .LBB0_448
	v_lshl_add_u64 v[168:169], v[2:3], 0, v[184:185]
	v_and_b32_e32 v3, 64, v223
	v_xor_b32_e32 v2, 32, v223
	v_add_u32_e32 v3, 64, v3
	s_lshr_b32 s3, s11, 3
	v_cmp_lt_i32_e32 vcc, v2, v3
	v_mul_f32_e32 v163, 0x3fb8aa3b, v4
	s_and_b32 s3, s3, 31
	v_cndmask_b32_e32 v2, v223, v2, vcc
	v_mov_b32_e32 v68, v66
	v_mov_b32_e32 v69, v66
	v_mov_b32_e32 v70, v66
	v_mov_b32_e32 v71, v66
	v_mov_b32_e32 v72, v66
	v_mov_b32_e32 v73, v66
	v_mov_b32_e32 v74, v66
	v_mov_b32_e32 v75, v66
	v_mov_b32_e32 v76, v66
	v_mov_b32_e32 v77, v66
	v_mov_b32_e32 v78, v66
	v_mov_b32_e32 v79, v66
	v_mov_b32_e32 v80, v66
	v_mov_b32_e32 v81, v66
	v_xor_b32_e32 v84, 0x80000000, v163
	v_lshl_or_b32 v4, s3, 7, v173
	s_and_b32 s23, s11, 0xffffff00
	v_lshlrev_b32_e32 v165, 2, v2
	v_lshl_add_u32 v2, s16, 6, v174
	s_sub_i32 s25, s16, s25
	v_mov_b32_e32 v67, v66
	v_mov_b32_e32 v34, 0
	v_mov_b64_e32 v[82:83], v[80:81]
	s_add_i32 s22, s17, 4
	s_addk_i32 s23, 0x3000
	v_lshl_add_u64 v[166:167], v[158:159], 1, s[20:21]
	s_mov_b32 s27, 0
	v_sub_u32_e32 v175, v2, v4
	s_addk_i32 s25, 0x42
	v_mov_b32_e32 v2, v185
	v_mov_b32_e32 v3, v185
	v_mov_b32_e32 v4, v185
	v_mov_b32_e32 v5, v185
	v_mov_b32_e32 v6, v185
	v_mov_b32_e32 v7, v185
	v_mov_b32_e32 v8, v185
	v_mov_b32_e32 v9, v185
	v_mov_b32_e32 v10, v185
	v_mov_b32_e32 v11, v185
	v_mov_b32_e32 v12, v185
	v_mov_b32_e32 v13, v185
	v_mov_b32_e32 v14, v185
	v_mov_b32_e32 v15, v185
	v_mov_b32_e32 v16, v185
	v_mov_b32_e32 v17, v185
	v_mov_b32_e32 v18, v185
	v_mov_b32_e32 v19, v185
	v_mov_b32_e32 v20, v185
	v_mov_b32_e32 v21, v185
	v_mov_b32_e32 v22, v185
	v_mov_b32_e32 v23, v185
	v_mov_b32_e32 v24, v185
	v_mov_b32_e32 v25, v185
	v_mov_b32_e32 v26, v185
	v_mov_b32_e32 v27, v185
	v_mov_b32_e32 v28, v185
	v_mov_b32_e32 v29, v185
	v_mov_b32_e32 v30, v185
	v_mov_b32_e32 v31, v185
	v_mov_b32_e32 v32, v185
	v_mov_b32_e32 v33, v185
	v_mov_b64_e32 v[80:81], v[78:79]
	v_mov_b64_e32 v[78:79], v[76:77]
	v_mov_b64_e32 v[76:77], v[74:75]
	v_mov_b64_e32 v[74:75], v[72:73]
	v_mov_b64_e32 v[72:73], v[70:71]
	v_mov_b64_e32 v[70:71], v[68:69]
	v_mov_b64_e32 v[68:69], v[66:67]
	v_mov_b32_e32 v85, v84
	v_mov_b32_e32 v86, v84
	v_mov_b32_e32 v87, v84
	v_mov_b32_e32 v88, v84
	v_mov_b32_e32 v89, v84
	v_mov_b32_e32 v90, v84
	v_mov_b32_e32 v91, v84
	v_mov_b32_e32 v92, v84
	v_mov_b32_e32 v93, v84
	v_mov_b32_e32 v94, v84
	v_mov_b32_e32 v95, v84
	v_mov_b32_e32 v96, v84
	v_mov_b32_e32 v97, v84
	v_mov_b32_e32 v98, v84
	v_mov_b32_e32 v99, v84
	v_mov_b32_e32 v35, v34
	v_mov_b32_e32 v36, v34
	v_mov_b32_e32 v37, v34
	v_mov_b32_e32 v38, v34
	v_mov_b32_e32 v39, v34
	v_mov_b32_e32 v40, v34
	v_mov_b32_e32 v41, v34
	v_mov_b32_e32 v42, v34
	v_mov_b32_e32 v43, v34
	v_mov_b32_e32 v44, v34
	v_mov_b32_e32 v45, v34
	v_mov_b32_e32 v46, v34
	v_mov_b32_e32 v47, v34
	v_mov_b32_e32 v48, v34
	v_mov_b32_e32 v49, v34
	v_mov_b32_e32 v50, v34
	v_mov_b32_e32 v51, v34
	v_mov_b32_e32 v52, v34
	v_mov_b32_e32 v53, v34
	v_mov_b32_e32 v54, v34
	v_mov_b32_e32 v55, v34
	v_mov_b32_e32 v56, v34
	v_mov_b32_e32 v57, v34
	v_mov_b32_e32 v58, v34
	v_mov_b32_e32 v59, v34
	v_mov_b32_e32 v60, v34
	v_mov_b32_e32 v61, v34
	v_mov_b32_e32 v62, v34
	v_mov_b32_e32 v63, v34
	v_mov_b32_e32 v64, v34
	v_mov_b32_e32 v65, v34
	s_cmp_lg_u32 s101, 0
	s_cbranch_scc1 .Lattn_bf_loop

.Lattn_b_rescale:
	v_max_f32_e32 v245, 0, v244
	v_exp_f32_e64 v246, -v245
	v_add_f32_e32 v163, v163, v245
	v_sub_f32_e32 v100, v100, v245
	v_sub_f32_e32 v101, v101, v245
	v_sub_f32_e32 v102, v102, v245
	v_sub_f32_e32 v103, v103, v245
	v_sub_f32_e32 v104, v104, v245
	v_sub_f32_e32 v105, v105, v245
	v_sub_f32_e32 v106, v106, v245
	v_sub_f32_e32 v107, v107, v245
	v_sub_f32_e32 v108, v108, v245
	v_sub_f32_e32 v109, v109, v245
	v_sub_f32_e32 v110, v110, v245
	v_sub_f32_e32 v111, v111, v245
	v_sub_f32_e32 v112, v112, v245
	v_sub_f32_e32 v113, v113, v245
	v_sub_f32_e32 v114, v114, v245
	v_sub_f32_e32 v115, v115, v245
	v_sub_f32_e32 v116, v116, v245
	v_sub_f32_e32 v117, v117, v245
	v_sub_f32_e32 v118, v118, v245
	v_sub_f32_e32 v119, v119, v245
	v_sub_f32_e32 v120, v120, v245
	v_sub_f32_e32 v121, v121, v245
	v_sub_f32_e32 v122, v122, v245
	v_sub_f32_e32 v123, v123, v245
	v_sub_f32_e32 v124, v124, v245
	v_sub_f32_e32 v125, v125, v245
	v_sub_f32_e32 v126, v126, v245
	v_sub_f32_e32 v127, v127, v245
	v_sub_f32_e32 v128, v128, v245
	v_sub_f32_e32 v129, v129, v245
	v_sub_f32_e32 v130, v130, v245
	v_sub_f32_e32 v131, v131, v245
	v_mul_f32_e32 v2, v2, v246
	v_mul_f32_e32 v3, v3, v246
	v_mul_f32_e32 v4, v4, v246
	v_mul_f32_e32 v5, v5, v246
	v_mul_f32_e32 v6, v6, v246
	v_mul_f32_e32 v7, v7, v246
	v_mul_f32_e32 v8, v8, v246
	v_mul_f32_e32 v9, v9, v246
	v_mul_f32_e32 v10, v10, v246
	v_mul_f32_e32 v11, v11, v246
	v_mul_f32_e32 v12, v12, v246
	v_mul_f32_e32 v13, v13, v246
	v_mul_f32_e32 v14, v14, v246
	v_mul_f32_e32 v15, v15, v246
	v_mul_f32_e32 v16, v16, v246
	v_mul_f32_e32 v17, v17, v246
	v_mul_f32_e32 v18, v18, v246
	v_mul_f32_e32 v19, v19, v246
	v_mul_f32_e32 v20, v20, v246
	v_mul_f32_e32 v21, v21, v246
	v_mul_f32_e32 v22, v22, v246
	v_mul_f32_e32 v23, v23, v246
	v_mul_f32_e32 v24, v24, v246
	v_mul_f32_e32 v25, v25, v246
	v_mul_f32_e32 v26, v26, v246
	v_mul_f32_e32 v27, v27, v246
	v_mul_f32_e32 v28, v28, v246
	v_mul_f32_e32 v29, v29, v246
	v_mul_f32_e32 v30, v30, v246
	v_mul_f32_e32 v31, v31, v246
	v_mul_f32_e32 v32, v32, v246
	v_mul_f32_e32 v33, v33, v246
	v_mul_f32_e32 v68, v68, v246
	v_mul_f32_e32 v69, v69, v246
	v_mul_f32_e32 v70, v70, v246
	v_mul_f32_e32 v71, v71, v246
	v_mul_f32_e32 v72, v72, v246
	v_mul_f32_e32 v73, v73, v246
	v_mul_f32_e32 v74, v74, v246
	v_mul_f32_e32 v75, v75, v246
	v_mul_f32_e32 v76, v76, v246
	v_mul_f32_e32 v77, v77, v246
	v_mul_f32_e32 v78, v78, v246
	v_mul_f32_e32 v79, v79, v246
	v_mul_f32_e32 v80, v80, v246
	v_mul_f32_e32 v81, v81, v246
	v_mul_f32_e32 v82, v82, v246
	v_mul_f32_e32 v83, v83, v246
	v_xor_b32_e32 v84, 0x80000000, v163
	v_mov_b32_e32 v85, v84
	v_mov_b32_e32 v86, v84
	v_mov_b32_e32 v87, v84
	v_mov_b32_e32 v88, v84
	v_mov_b32_e32 v89, v84
	v_mov_b32_e32 v90, v84
	v_mov_b32_e32 v91, v84
	v_mov_b32_e32 v92, v84
	v_mov_b32_e32 v93, v84
	v_mov_b32_e32 v94, v84
	v_mov_b32_e32 v95, v84
	v_mov_b32_e32 v96, v84
	v_mov_b32_e32 v97, v84
	v_mov_b32_e32 v98, v84
	v_mov_b32_e32 v99, v84
	s_branch .Lattn_b_exp
.Lattn_bf_loop:
	s_add_i32 s26, s27, 1
	s_cmp_ge_i32 s26, s22
	s_cselect_b64 s[20:21], -1, 0
	s_bitcmp1_b32 s27, 0
	s_cselect_b32 s3, 0x2400, 0
	v_add_u32_e32 v67, s3, v172
	s_cmp_ge_i32 s27, s17
	s_cbranch_scc1 .Lattn_bf_go
	v_readfirstlane_b32 s3, v175
	s_nop 3
	s_cmp_ge_i32 s3, 31
	s_cbranch_scc1 .Lattn_bf_skip
	s_cmp_lt_i32 s3, 0xfffffebf
	s_cbranch_scc1 .Lattn_bf_skip

.Lattn_bf_max:
	s_nop 9
	v_exp_f32_e32 v100, v100
	v_exp_f32_e32 v101, v101
	v_exp_f32_e32 v102, v102
	v_exp_f32_e32 v103, v103
	v_exp_f32_e32 v104, v104
	v_exp_f32_e32 v105, v105
	v_exp_f32_e32 v106, v106
	v_exp_f32_e32 v107, v107
	v_cvt_pk_bf16_f32 v100, v100, v101
	v_cvt_pk_bf16_f32 v101, v102, v103
	v_cvt_pk_bf16_f32 v102, v104, v105
	v_cvt_pk_bf16_f32 v103, v106, v107
	s_mov_b32 s65, s64
	v_mov_b64_e32 v[176:177], s[64:65]
	v_mov_b64_e32 v[178:179], s[64:65]
	s_waitcnt lgkmcnt(7)
	v_mfma_f32_32x32x16_bf16 v[2:17], v[34:37], v[100:103], v[2:17]
	v_exp_f32_e32 v108, v108
	v_exp_f32_e32 v109, v109
	v_exp_f32_e32 v110, v110
	v_exp_f32_e32 v111, v111
	s_waitcnt lgkmcnt(6)
	v_mfma_f32_32x32x16_bf16 v[18:33], v[38:41], v[100:103], v[18:33]
	v_exp_f32_e32 v112, v112
	v_exp_f32_e32 v113, v113
	v_exp_f32_e32 v114, v114
	v_exp_f32_e32 v115, v115
	v_cvt_pk_bf16_f32 v104, v108, v109
	v_cvt_pk_bf16_f32 v105, v110, v111
	v_cvt_pk_bf16_f32 v106, v112, v113
	v_cvt_pk_bf16_f32 v107, v114, v115
	s_nop 1
	s_waitcnt lgkmcnt(5)
	v_mfma_f32_32x32x16_bf16 v[2:17], v[42:45], v[104:107], v[2:17]
	v_exp_f32_e32 v116, v116
	v_exp_f32_e32 v117, v117
	v_exp_f32_e32 v118, v118
	v_exp_f32_e32 v119, v119
	s_waitcnt lgkmcnt(4)
	v_mfma_f32_32x32x16_bf16 v[18:33], v[46:49], v[104:107], v[18:33]
	v_exp_f32_e32 v120, v120
	v_exp_f32_e32 v121, v121
	v_exp_f32_e32 v122, v122
	v_exp_f32_e32 v123, v123
	v_cvt_pk_bf16_f32 v108, v116, v117
	v_cvt_pk_bf16_f32 v109, v118, v119
	v_cvt_pk_bf16_f32 v110, v120, v121
	v_cvt_pk_bf16_f32 v111, v122, v123
	s_nop 1
	s_waitcnt lgkmcnt(3)
	v_mfma_f32_32x32x16_bf16 v[2:17], v[50:53], v[108:111], v[2:17]
	v_exp_f32_e32 v124, v124
	v_exp_f32_e32 v125, v125
	v_exp_f32_e32 v126, v126
	v_exp_f32_e32 v127, v127
	s_waitcnt lgkmcnt(2)
	v_mfma_f32_32x32x16_bf16 v[18:33], v[54:57], v[108:111], v[18:33]
	v_exp_f32_e32 v128, v128
	v_exp_f32_e32 v129, v129
	v_exp_f32_e32 v130, v130
	v_exp_f32_e32 v131, v131
	v_cvt_pk_bf16_f32 v112, v124, v125
	v_cvt_pk_bf16_f32 v113, v126, v127
	v_cvt_pk_bf16_f32 v114, v128, v129
	v_cvt_pk_bf16_f32 v115, v130, v131
	s_nop 1
	s_waitcnt lgkmcnt(1)
	v_mfma_f32_32x32x16_bf16 v[2:17], v[58:61], v[112:115], v[2:17]
	s_waitcnt lgkmcnt(0)
	s_barrier
	v_mfma_f32_32x32x16_bf16 v[18:33], v[62:65], v[112:115], v[18:33]
	v_mfma_f32_32x32x16_bf16 v[68:83], v[176:179], v[100:103], v[68:83]
	v_mfma_f32_32x32x16_bf16 v[68:83], v[176:179], v[104:107], v[68:83]
	v_mfma_f32_32x32x16_bf16 v[68:83], v[176:179], v[108:111], v[68:83]
	v_mfma_f32_32x32x16_bf16 v[68:83], v[176:179], v[112:115], v[68:83]

.Lattn_bf_skip:
	s_bitcmp1_b32 s26, 0
	s_cselect_b32 s3, 0x2400, 0
	v_add_u32_e32 v254, s3, v170
	v_add_u32_e32 v255, s3, v171
	v_add_u32_e32 v255, 0x4800, v255
	s_waitcnt vmcnt(0)
	ds_write_b128 v254, v[148:151]
	ds_write2_b64 v255, v[152:153], v[154:155] offset1:2
	s_add_i32 s28, s27, 2
	s_add_i32 s3, s16, s27
	s_add_i32 s3, s3, 2
	s_add_i32 s29, s25, s27
	s_cmp_lt_i32 s28, s17
	s_cselect_b32 s3, s3, s29
	s_lshl_b32 s28, s3, 6
	s_cmp_lt_i32 s3, 64
	s_cselect_b32 s3, s24, s23
	s_add_i32 s3, s3, s28
	v_add_u32_e32 v248, s3, v157
	v_mad_i64_i32 v[250:251], s[30:31], v248, s60, v[166:167]
	s_ashr_i32 s29, s28, 31
	v_lshl_add_u64 v[252:253], s[28:29], 1, v[168:169]
	global_load_dwordx4 v[148:151], v[250:251], off
	global_load_dwordx4 v[152:155], v[252:253], off
	s_waitcnt lgkmcnt(0)
	s_barrier
	s_branch .Lattn_bf_next
.LBB0_470:
	s_mov_b64 s[4:5], 0
	s_mov_b32 s6, s34
